# step-0 pointer fetches between weight conversions read the LDS pointer table with ds_read_b64 (lgkmcnt wait) instead of a flat load with vmcnt(0), so outstanding stores are not drained
# baseline (speedup 1.0000x reference)
; #define TIDX tid_opaque()
; __device__ __forceinline__ const void* ldp(int i) {
;     const unsigned long long v = *(const volatile unsigned long long*)(g_smem + PTR_OFF + 8 * i);
;     const unsigned lo = __builtin_amdgcn_readfirstlane((unsigned)v), hi = __builtin_amdgcn_readfirstlane((unsigned)(v >> 32));
;     return (const void*)(const __attribute__((address_space(1))) void*)(((unsigned long long)hi << 32) | lo);
; }
;     if (ld == 0) ld = K;
;     const int tid = TIDX, lane = tid & 63, w = tid >> 6;
;     const int nkt = K / 64, ntile = (R / 64) * nkt;
;     const int first = ((int)blockIdx.x + rot) % (int)gridDim.x;
;     for (int t_ = first; t_ < ntile * ((REP & 1) + 1); t_ += gridDim.x) { const int t = t_ % ntile;
.LBB0_308:
	s_add_i32 s6, 0, 0x23e20
	s_cmp_lg_u32 s6, -1
	s_cselect_b32 s6, s6, 0
	s_cselect_b32 s7, s41, 0
	v_mov_b32_e32 v0, s6
	v_mov_b32_e32 v1, s7
	ds_read_b64 v[2:3], v0
	s_waitcnt lgkmcnt(0)
	v_readlane_b32 s7, v254, 58
	s_mul_hi_u32 s6, s7, s14
	s_mul_i32 s6, s6, s13
	s_sub_i32 s6, s7, s6
	s_sub_i32 s7, s6, s13
	s_cmp_ge_u32 s6, s13
	s_cselect_b32 s6, s7, s6
	s_sub_i32 s7, s6, s13
	s_cmp_ge_u32 s6, s13
	s_cselect_b32 s6, s7, s6
	v_readlane_b32 s7, v254, 57
	s_xor_b32 s6, s6, s7
	s_sub_i32 s11, s6, s7
	v_mov_b32_e32 v0, v234
	s_cmpk_gt_i32 s11, 0x2bf
	s_waitcnt lgkmcnt(0)
	v_readfirstlane_b32 s7, v3
	v_readfirstlane_b32 s6, v2
	s_cbranch_scc1 .LBB0_311
	v_and_b32_e32 v2, 63, v0
	s_lshl_b32 s8, s15, 2
	v_lshlrev_b32_e32 v184, 1, v2
	s_add_u32 s6, s6, s8
	v_ashrrev_i32_e32 v3, 6, v0
	v_lshl_add_u64 v[0:1], s[0:1], 0, v[184:185]
	s_mov_b64 s[8:9], 0xb00000
	v_lshl_add_u64 v[0:1], v[0:1], 0, s[8:9]
	s_movk_i32 s8, 0x104
	v_lshl_add_u32 v12, v2, 2, 0
	v_lshlrev_b32_e32 v4, 8, v2
	v_lshlrev_b32_e32 v5, 2, v3
	v_mul_lo_u32 v13, v3, s8
	s_addc_u32 s7, s7, 0
	v_add3_u32 v4, v12, v4, v5
	v_add_u32_e32 v5, 8, v3
	v_add_u32_e32 v6, 16, v3
	v_add_u32_e32 v7, 24, v3
	v_add_u32_e32 v8, 32, v3
	v_add_u32_e32 v9, 40, v3
	v_add_u32_e32 v10, 48, v3
	v_add_u32_e32 v11, 56, v3
	v_add_u32_e32 v12, v12, v13

; __device__ void convert_phase(unsigned char* smem, const Params& p, int l) {
;     ...
;     { const float* wi = ((const float*)ldp(6)) + (size_t)l * DM * INC; const float* gn = ((const float*)ldp(5)) + l * DM;
;       conv_tiles(tile, wt + W_HYRG, 2560, 1024, 71, [=](int k, int r) { const int col = r < HYC ? r : r + QKVC; return gn[k] * wi[(size_t)k * INC + col]; });
.LBB0_311:
	s_add_i32 s6, 0, 0x23e30
	s_cmp_lg_u32 s6, -1
	s_cselect_b32 s6, s6, 0
	s_cselect_b32 s7, s41, 0
	v_mov_b32_e32 v0, s6
	v_mov_b32_e32 v1, s7
	ds_read_b64 v[0:1], v0
	s_waitcnt lgkmcnt(0)
	s_mul_i32 s6, s12, 0x1c00000
	v_readlane_b32 s18, v254, 60
	s_mov_b32 s22, 0x7f800000
	s_waitcnt lgkmcnt(0)
	v_readfirstlane_b32 s8, v0
	v_readfirstlane_b32 s7, v1
	s_add_u32 s6, s8, s6
	s_addc_u32 s7, s7, 0
	s_add_i32 s17, 0, 0x23e28
	s_cmp_lg_u32 s17, -1
	s_cselect_b32 s8, s17, 0
	s_cselect_b32 s9, s41, 0
	v_mov_b32_e32 v0, s8
	v_mov_b32_e32 v1, s9
	ds_read_b64 v[2:3], v0
	s_waitcnt lgkmcnt(0)
	s_mul_hi_u32 s8, s18, s14
	s_mul_i32 s11, s8, s13
	s_lshl_b32 s16, s10, 2
	v_mov_b32_e32 v0, v234
	s_waitcnt lgkmcnt(0)
	v_readfirstlane_b32 s8, v2
	v_readfirstlane_b32 s9, v3
	s_add_u32 s8, s8, s16
	s_addc_u32 s9, s9, 0
	s_sub_i32 s10, s18, s11
	s_sub_i32 s11, s10, s13
	s_cmp_ge_u32 s10, s13
	s_cselect_b32 s10, s11, s10
	s_sub_i32 s11, s10, s13
	s_cmp_ge_u32 s10, s13
	s_cselect_b32 s10, s11, s10
	v_readlane_b32 s11, v254, 59
	s_xor_b32 s10, s10, s11
	s_sub_i32 s18, s10, s11
	s_cmpk_gt_i32 s18, 0x27f
	s_cbranch_scc1 .LBB0_314
	v_and_b32_e32 v2, 63, v0
	v_lshlrev_b32_e32 v184, 1, v2
	v_ashrrev_i32_e32 v3, 6, v0
	v_lshl_add_u64 v[0:1], s[0:1], 0, v[184:185]
	s_mov_b64 s[10:11], 0x1080000
	v_lshl_add_u64 v[0:1], v[0:1], 0, s[10:11]
	s_movk_i32 s10, 0x104
	v_lshl_add_u32 v12, v2, 2, 0
	v_lshlrev_b32_e32 v4, 8, v2
	v_lshlrev_b32_e32 v5, 2, v3
	v_mul_lo_u32 v13, v3, s10
	v_add3_u32 v4, v12, v4, v5
	v_add_u32_e32 v5, 8, v3
	v_add_u32_e32 v6, 16, v3
	v_add_u32_e32 v7, 24, v3
	v_add_u32_e32 v8, 32, v3
	v_add_u32_e32 v9, 40, v3
	v_add_u32_e32 v10, 48, v3
	v_add_u32_e32 v11, 56, v3
	v_add_u32_e32 v12, v12, v13

; __device__ void convert_phase(unsigned char* smem, const Params& p, int l) {
;     ...
;     { const float* wgt = ((const float*)ldp(26)) + (size_t)l * DM * 3072; const float* gn = ((const float*)ldp(5)) + l * DM; conv_tiles(tile, wt + W_GATE, 3072, 1024, 151, [=](int k, int r) { return gn[k] * wgt[(size_t)k * 3072 + r]; }); }
.LBB0_317:
	s_add_i32 s6, 0, 0x23ed0
	s_cmp_lg_u32 s6, -1
	s_cselect_b32 s6, s6, 0
	s_cselect_b32 s7, s41, 0
	s_cmp_lg_u32 s17, -1
	v_mov_b32_e32 v0, s6
	v_mov_b32_e32 v1, s7
	s_cselect_b32 s6, s17, 0
	s_cselect_b32 s7, s41, 0
	ds_read_b64 v[2:3], v0
	s_waitcnt lgkmcnt(0)
	v_mov_b32_e32 v0, s6
	v_mov_b32_e32 v1, s7
	ds_read_b64 v[4:5], v0
	s_waitcnt lgkmcnt(0)
	v_readlane_b32 s7, v255, 0
	s_mul_hi_u32 s6, s7, s14
	s_mul_i32 s6, s6, s13
	s_sub_i32 s6, s7, s6
	s_sub_i32 s7, s6, s13
	s_cmp_ge_u32 s6, s13
	s_cselect_b32 s6, s7, s6
	s_sub_i32 s7, s6, s13
	s_cmp_ge_u32 s6, s13
	s_cselect_b32 s6, s7, s6
	v_readlane_b32 s7, v254, 63
	s_xor_b32 s6, s6, s7
	s_sub_i32 s17, s6, s7
	v_mov_b32_e32 v0, v234
	s_cmpk_gt_i32 s17, 0x2ff
	s_waitcnt lgkmcnt(0)
	v_readfirstlane_b32 s7, v3
	v_readfirstlane_b32 s6, v2
	v_readfirstlane_b32 s9, v5
	v_readfirstlane_b32 s8, v4
	s_cbranch_scc1 .LBB0_320
	v_and_b32_e32 v2, 63, v0
	s_mul_i32 s10, s12, 0xc00000
	v_lshlrev_b32_e32 v184, 1, v2
	s_add_u32 s6, s6, s10
	v_ashrrev_i32_e32 v3, 6, v0
	v_lshl_add_u64 v[0:1], s[0:1], 0, v[184:185]
	s_mov_b64 s[10:11], 0x1e80000
	s_addc_u32 s7, s7, 0
	v_lshl_add_u64 v[0:1], v[0:1], 0, s[10:11]
	s_movk_i32 s10, 0x104
	s_add_u32 s8, s8, s16
	v_lshl_add_u32 v12, v2, 2, 0
	v_lshlrev_b32_e32 v4, 8, v2
	v_lshlrev_b32_e32 v5, 2, v3
	v_mul_lo_u32 v13, v3, s10
	s_addc_u32 s9, s9, 0
	v_add3_u32 v4, v12, v4, v5
	v_add_u32_e32 v5, 8, v3
	v_add_u32_e32 v6, 16, v3
	v_add_u32_e32 v7, 24, v3
	v_add_u32_e32 v8, 32, v3
	v_add_u32_e32 v9, 40, v3
	v_add_u32_e32 v10, 48, v3
	v_add_u32_e32 v11, 56, v3
	v_add_u32_e32 v12, v12, v13

; __device__ void convert_phase(unsigned char* smem, const Params& p, int l) {
;     ...
;     { const float* a = ((const float*)ldp(28)) + (size_t)l * 512 * DM; conv_tiles(tile, wt + W_PCAT + 0, 1024, 512, 193, [=](int k, int r) { return a[(size_t)k * DM + r]; }, 1536); }
.LBB0_320:
	s_add_i32 s6, 0, 0x23ee0
	s_cmp_lg_u32 s6, -1
	s_cselect_b32 s6, s6, 0
	s_cselect_b32 s7, s41, 0
	v_mov_b32_e32 v0, s6
	v_mov_b32_e32 v1, s7
	ds_read_b64 v[2:3], v0
	s_waitcnt lgkmcnt(0)
	v_readlane_b32 s7, v255, 2
	s_mul_hi_u32 s6, s7, s14
	s_mul_i32 s6, s6, s13
	s_sub_i32 s6, s7, s6
	s_lshl_b32 s10, s12, 19
	s_sub_i32 s7, s6, s13
	s_cmp_ge_u32 s6, s13
	s_cselect_b32 s6, s7, s6
	s_sub_i32 s7, s6, s13
	s_cmp_ge_u32 s6, s13
	s_cselect_b32 s6, s7, s6
	v_readlane_b32 s7, v255, 1
	s_xor_b32 s6, s6, s7
	s_sub_i32 s11, s6, s7
	v_mov_b32_e32 v0, v234
	s_cmpk_gt_i32 s11, 0x7f
	s_waitcnt lgkmcnt(0)
	v_readfirstlane_b32 s7, v3
	v_readfirstlane_b32 s6, v2
	s_cbranch_scc1 .LBB0_323
	v_and_b32_e32 v2, 63, v0
	s_lshl_b32 s8, s10, 2
	v_lshlrev_b32_e32 v184, 1, v2
	s_add_u32 s6, s6, s8
	v_ashrrev_i32_e32 v3, 6, v0
	v_lshl_add_u64 v[0:1], s[0:1], 0, v[184:185]
	s_mov_b64 s[8:9], 0x2480000
	v_lshl_add_u64 v[0:1], v[0:1], 0, s[8:9]
	s_movk_i32 s8, 0x104
	v_lshl_add_u32 v12, v2, 2, 0
	v_lshlrev_b32_e32 v4, 8, v2
	v_lshlrev_b32_e32 v5, 2, v3
	v_mul_lo_u32 v13, v3, s8
	s_addc_u32 s7, s7, 0
	v_add3_u32 v4, v12, v4, v5
	v_add_u32_e32 v5, 8, v3
	v_add_u32_e32 v6, 16, v3
	v_add_u32_e32 v7, 24, v3
	v_add_u32_e32 v8, 32, v3
	v_add_u32_e32 v9, 40, v3
	v_add_u32_e32 v10, 48, v3
	v_add_u32_e32 v11, 56, v3
	v_add_u32_e32 v12, v12, v13

; __device__ void convert_phase(unsigned char* smem, const Params& p, int l) {
;     ...
;     { const float* a = ((const float*)ldp(29)) + (size_t)l * 512 * DM; conv_tiles(tile, wt + W_PCAT + 512, 1024, 512, 211, [=](int k, int r) { return a[(size_t)k * DM + r]; }, 1536); }
.LBB0_323:
	s_add_i32 s6, 0, 0x23ee8
	s_cmp_lg_u32 s6, -1
	s_cselect_b32 s6, s6, 0
	s_cselect_b32 s7, s41, 0
	v_mov_b32_e32 v0, s6
	v_mov_b32_e32 v1, s7
	ds_read_b64 v[2:3], v0
	s_waitcnt lgkmcnt(0)
	v_readlane_b32 s7, v255, 4
	s_mul_hi_u32 s6, s7, s14
	s_mul_i32 s6, s6, s13
	s_sub_i32 s6, s7, s6
	s_sub_i32 s7, s6, s13
	s_cmp_ge_u32 s6, s13
	s_cselect_b32 s6, s7, s6
	s_sub_i32 s7, s6, s13
	s_cmp_ge_u32 s6, s13
	s_cselect_b32 s6, s7, s6
	v_readlane_b32 s7, v255, 3
	s_xor_b32 s6, s6, s7
	s_sub_i32 s11, s6, s7
	v_mov_b32_e32 v0, v234
	s_cmpk_gt_i32 s11, 0x7f
	s_waitcnt lgkmcnt(0)
	v_readfirstlane_b32 s7, v3
	v_readfirstlane_b32 s6, v2
	s_cbranch_scc1 .LBB0_326
	v_and_b32_e32 v2, 63, v0
	s_lshl_b32 s8, s10, 2
	v_lshlrev_b32_e32 v184, 1, v2
	s_add_u32 s6, s6, s8
	v_ashrrev_i32_e32 v3, 6, v0
	v_lshl_add_u64 v[0:1], s[0:1], 0, v[184:185]
	s_mov_b64 s[8:9], 0x2480400
	v_lshl_add_u64 v[0:1], v[0:1], 0, s[8:9]
	s_movk_i32 s8, 0x104
	v_lshl_add_u32 v12, v2, 2, 0
	v_lshlrev_b32_e32 v4, 8, v2
	v_lshlrev_b32_e32 v5, 2, v3
	v_mul_lo_u32 v13, v3, s8
	s_addc_u32 s7, s7, 0
	v_add3_u32 v4, v12, v4, v5
	v_add_u32_e32 v5, 8, v3
	v_add_u32_e32 v6, 16, v3
	v_add_u32_e32 v7, 24, v3
	v_add_u32_e32 v8, 32, v3
	v_add_u32_e32 v9, 40, v3
	v_add_u32_e32 v10, 48, v3
	v_add_u32_e32 v11, 56, v3
	v_add_u32_e32 v12, v12, v13

; __device__ void convert_phase(unsigned char* smem, const Params& p, int l) {
;     ...
;     { const float* a = ((const float*)ldp(30)) + (size_t)l * 512 * DM; conv_tiles(tile, wt + W_PCAT + 1024, 1024, 512, 229, [=](int k, int r) { return a[(size_t)k * DM + r]; }, 1536); }
.LBB0_326:
	s_add_i32 s6, 0, 0x23ef0
	s_cmp_lg_u32 s6, -1
	s_cselect_b32 s6, s6, 0
	s_cselect_b32 s7, s41, 0
	v_mov_b32_e32 v0, s6
	v_mov_b32_e32 v1, s7
	ds_read_b64 v[2:3], v0
	s_waitcnt lgkmcnt(0)
	v_readlane_b32 s7, v255, 6
	s_mul_hi_u32 s6, s7, s14
	s_mul_i32 s6, s6, s13
	s_sub_i32 s6, s7, s6
	s_sub_i32 s7, s6, s13
	s_cmp_ge_u32 s6, s13
	s_cselect_b32 s6, s7, s6
	s_sub_i32 s7, s6, s13
	s_cmp_ge_u32 s6, s13
	s_cselect_b32 s6, s7, s6
	v_readlane_b32 s7, v255, 5
	s_xor_b32 s6, s6, s7
	s_sub_i32 s11, s6, s7
	v_mov_b32_e32 v0, v234
	s_cmpk_gt_i32 s11, 0x7f
	s_waitcnt lgkmcnt(0)
	v_readfirstlane_b32 s7, v3
	v_readfirstlane_b32 s6, v2
	s_cbranch_scc1 .LBB0_329
	v_and_b32_e32 v2, 63, v0
	s_lshl_b32 s8, s10, 2
	v_lshlrev_b32_e32 v184, 1, v2
	s_add_u32 s6, s6, s8
	v_ashrrev_i32_e32 v3, 6, v0
	v_lshl_add_u64 v[0:1], s[0:1], 0, v[184:185]
	s_mov_b64 s[8:9], 0x2480800
	v_lshl_add_u64 v[0:1], v[0:1], 0, s[8:9]
	s_movk_i32 s8, 0x104
	v_lshl_add_u32 v12, v2, 2, 0
	v_lshlrev_b32_e32 v4, 8, v2
	v_lshlrev_b32_e32 v5, 2, v3
	v_mul_lo_u32 v13, v3, s8
	s_addc_u32 s7, s7, 0
	v_add3_u32 v4, v12, v4, v5
	v_add_u32_e32 v5, 8, v3
	v_add_u32_e32 v6, 16, v3
	v_add_u32_e32 v7, 24, v3
	v_add_u32_e32 v8, 32, v3
	v_add_u32_e32 v9, 40, v3
	v_add_u32_e32 v10, 48, v3
	v_add_u32_e32 v11, 56, v3
	v_add_u32_e32 v12, v12, v13

; __device__ void convert_phase(unsigned char* smem, const Params& p, int l) {
;     ...
;     { const float* a = ((const float*)ldp(31)) + (size_t)l * DM * DM; conv_tiles(tile, wt + W_OUT, 1024, 1024, 17, [=](int k, int r) { return a[(size_t)k * DM + r]; }); }
.LBB0_329:
	s_add_i32 s6, 0, 0x23ef8
	s_cmp_lg_u32 s6, -1
	s_cselect_b32 s6, s6, 0
	s_cselect_b32 s7, s41, 0
	v_mov_b32_e32 v0, s6
	v_mov_b32_e32 v1, s7
	ds_read_b64 v[2:3], v0
	s_waitcnt lgkmcnt(0)
	v_readlane_b32 s7, v255, 8
	s_mul_hi_u32 s6, s7, s14
	s_mul_i32 s6, s6, s13
	s_sub_i32 s6, s7, s6
	s_sub_i32 s7, s6, s13
	s_cmp_ge_u32 s6, s13
	s_cselect_b32 s6, s7, s6
	s_sub_i32 s7, s6, s13
	s_cmp_ge_u32 s6, s13
	s_cselect_b32 s6, s7, s6
	v_readlane_b32 s7, v255, 7
	s_xor_b32 s6, s6, s7
	s_sub_i32 s10, s6, s7
	v_mov_b32_e32 v0, v234
	s_cmpk_gt_i32 s10, 0xff
	s_waitcnt lgkmcnt(0)
	v_readfirstlane_b32 s7, v3
	v_readfirstlane_b32 s6, v2
	s_cbranch_scc1 .LBB0_332
	v_and_b32_e32 v2, 63, v0
	s_lshl_b32 s8, s12, 22
	v_lshlrev_b32_e32 v184, 1, v2
	s_add_u32 s6, s6, s8
	v_ashrrev_i32_e32 v3, 6, v0
	v_lshl_add_u64 v[0:1], s[0:1], 0, v[184:185]
	s_mov_b64 s[8:9], 0x2780000
	v_lshl_add_u64 v[0:1], v[0:1], 0, s[8:9]
	s_movk_i32 s8, 0x104
	v_lshl_add_u32 v12, v2, 2, 0
	v_lshlrev_b32_e32 v4, 8, v2
	v_lshlrev_b32_e32 v5, 2, v3
	v_mul_lo_u32 v13, v3, s8
	s_addc_u32 s7, s7, 0
	v_add3_u32 v4, v12, v4, v5
	v_add_u32_e32 v5, 8, v3
	v_add_u32_e32 v6, 16, v3
	v_add_u32_e32 v7, 24, v3
	v_add_u32_e32 v8, 32, v3
	v_add_u32_e32 v9, 40, v3
	v_add_u32_e32 v10, 48, v3
	v_add_u32_e32 v11, 56, v3
	v_add_u32_e32 v12, v12, v13

; __device__ void convert_phase(unsigned char* smem, const Params& p, int l) {
;     ...
;     { const float* wg = ((const float*)ldp(33)) + uo; const float* wu = ((const float*)ldp(34)) + uo; const float* gn = ((const float*)ldp(32)) + l * DM;
;       conv_tiles(tile, wt + W_UP2, 5632, 1024, 53, [=](int k, int r) { const int col = (r >> 5) * 16 + (r & 15); return gn[k] * (((r >> 4) & 1) ? wu[(size_t)k * DFF + col] : wg[(size_t)k * DFF + col]); }); }
.LBB0_332:
	s_add_i32 s6, 0, 0x23f08
	s_cmp_lg_u32 s6, -1
	s_cselect_b32 s6, s6, 0
	s_cselect_b32 s7, s41, 0
	v_mov_b32_e32 v0, s6
	s_add_i32 s6, 0, 0x23f10
	s_cmp_lg_u32 s6, -1
	v_mov_b32_e32 v1, s7
	s_cselect_b32 s6, s6, 0
	ds_read_b64 v[2:3], v0
	s_waitcnt lgkmcnt(0)
	s_cselect_b32 s7, s41, 0
	v_mov_b32_e32 v0, s6
	s_add_i32 s6, 0, 0x23f00
	s_cmp_lg_u32 s6, -1
	v_mov_b32_e32 v1, s7
	s_cselect_b32 s6, s6, 0
	s_cselect_b32 s7, s41, 0
	ds_read_b64 v[4:5], v0
	s_waitcnt lgkmcnt(0)
	v_mov_b32_e32 v0, s6
	v_mov_b32_e32 v1, s7
	ds_read_b64 v[6:7], v0
	s_waitcnt lgkmcnt(0)
	v_readlane_b32 s7, v255, 10
	s_mul_hi_u32 s6, s7, s14
	s_mul_i32 s6, s6, s13
	s_sub_i32 s6, s7, s6
	s_sub_i32 s7, s6, s13
	s_cmp_ge_u32 s6, s13
	s_cselect_b32 s6, s7, s6
	s_sub_i32 s7, s6, s13
	s_cmp_ge_u32 s6, s13
	s_cselect_b32 s6, s7, s6
	v_readlane_b32 s7, v255, 9
	s_xor_b32 s6, s6, s7
	s_sub_i32 s10, s6, s7
	v_mov_b32_e32 v0, v234
	s_cmpk_gt_i32 s10, 0x57f
	s_waitcnt lgkmcnt(0)
	v_readfirstlane_b32 s9, v3
	v_readfirstlane_b32 s8, v2
	v_readfirstlane_b32 s17, v5
	v_readfirstlane_b32 s11, v4
	v_readfirstlane_b32 s7, v7
	v_readfirstlane_b32 s6, v6
	s_cbranch_scc1 .LBB0_335
	v_and_b32_e32 v4, 63, v0
	v_ashrrev_i32_e32 v5, 6, v0
	v_and_b32_e32 v6, 15, v0
	v_and_b32_e32 v0, 16, v0
	v_mov_b32_e32 v1, s17
	v_mov_b32_e32 v2, s9
	v_cmp_eq_u32_e32 vcc, 0, v0
	v_mov_b32_e32 v0, s11
	v_lshlrev_b32_e32 v184, 1, v4
	v_cndmask_b32_e32 v1, v1, v2, vcc
	v_mov_b32_e32 v2, s8
	v_cndmask_b32_e32 v0, v0, v2, vcc
	v_lshl_add_u64 v[2:3], s[0:1], 0, v[184:185]
	s_mov_b64 s[8:9], 0x2980000
	s_add_u32 s6, s6, s16
	v_lshl_add_u64 v[2:3], v[2:3], 0, s[8:9]
	s_movk_i32 s8, 0x104
	s_addc_u32 s7, s7, 0
	s_lshl_b32 s24, s15, 2
	v_lshl_add_u32 v15, v4, 2, 0
	v_lshlrev_b32_e32 v7, 8, v4
	v_lshlrev_b32_e32 v8, 2, v5
	v_mul_lo_u32 v16, v5, s8
	v_lshl_add_u64 v[0:1], v[0:1], 0, s[24:25]
	v_add3_u32 v7, v15, v7, v8
	v_add_u32_e32 v8, 8, v5
	v_add_u32_e32 v9, 16, v5
	v_add_u32_e32 v10, 24, v5
	v_add_u32_e32 v11, 32, v5
	v_add_u32_e32 v12, 40, v5
	v_add_u32_e32 v13, 48, v5
	v_add_u32_e32 v14, 56, v5
	v_add_u32_e32 v15, v15, v16

; __device__ void convert_phase(unsigned char* smem, const Params& p, int l) {
;     ...
;     { const float* wd = ((const float*)ldp(35)) + uo; conv_tiles(tile, wt + W_DN2, 1024, 2816, 97, [=](int k, int r) { return wd[(size_t)k * DM + r]; }); }
.LBB0_335:
	s_add_i32 s6, 0, 0x23f18
	s_cmp_lg_u32 s6, -1
	s_cselect_b32 s6, s6, 0
	s_cselect_b32 s7, s41, 0
	v_mov_b32_e32 v0, s6
	v_mov_b32_e32 v1, s7
	ds_read_b64 v[2:3], v0
	s_waitcnt lgkmcnt(0)
	v_readlane_b32 s7, v255, 12
	s_mul_hi_u32 s6, s7, s14
	s_mul_i32 s6, s6, s13
	s_sub_i32 s6, s7, s6
	s_sub_i32 s7, s6, s13
	s_cmp_ge_u32 s6, s13
	s_cselect_b32 s6, s7, s6
	s_sub_i32 s7, s6, s13
	s_cmp_ge_u32 s6, s13
	s_cselect_b32 s6, s7, s6
	v_readlane_b32 s7, v255, 11
	s_xor_b32 s6, s6, s7
	s_sub_i32 s10, s6, s7
	v_mov_b32_e32 v0, v234
	s_cmpk_gt_i32 s10, 0x2bf
	s_waitcnt lgkmcnt(0)
	v_readfirstlane_b32 s7, v3
	v_readfirstlane_b32 s6, v2
	s_cbranch_scc1 .LBB0_338
	v_and_b32_e32 v2, 63, v0
	s_lshl_b32 s8, s15, 2
	v_lshlrev_b32_e32 v184, 1, v2
	s_add_u32 s6, s6, s8
	v_ashrrev_i32_e32 v3, 6, v0
	v_lshl_add_u64 v[0:1], s[0:1], 0, v[184:185]
	s_mov_b64 s[8:9], 0x3480000
	v_lshl_add_u64 v[0:1], v[0:1], 0, s[8:9]
	s_movk_i32 s8, 0x104
	v_lshl_add_u32 v12, v2, 2, 0
	v_lshlrev_b32_e32 v4, 8, v2
	v_lshlrev_b32_e32 v5, 2, v3
	v_mul_lo_u32 v13, v3, s8
	s_addc_u32 s7, s7, 0
	v_add3_u32 v4, v12, v4, v5
	v_add_u32_e32 v5, 8, v3
	v_add_u32_e32 v6, 16, v3
	v_add_u32_e32 v7, 24, v3
	v_add_u32_e32 v8, 32, v3
	v_add_u32_e32 v9, 40, v3
	v_add_u32_e32 v10, 48, v3
	v_add_u32_e32 v11, 56, v3
	v_add_u32_e32 v12, v12, v13

; __device__ void convert_phase(unsigned char* smem, const Params& p, int l) {
;     ...
;     { const float* wa = ((const float*)ldp(21)) + (size_t)l * 2 * 8 * 64 * 64; const float* wx = ((const float*)ldp(23)) + (size_t)l * 2 * 8 * 64 * 64;
;       conv_tiles(tile, wt + W_RG, 2048, 512, 131, [=](int k, int r) { const int dir = r >> 10, cp = r & 1023, ch = (cp >> 5) * 16 + (cp & 15), hb = ch >> 6, jj = ch & 63;
;           if ((k >> 6) != hb) return 0.0f; const float* src = ((cp >> 4) & 1) ? wx : wa; return src[(((size_t)dir * 8 + hb) * 64 + (k & 63)) * 64 + jj]; }); }
.LBB0_338:
	s_add_i32 s6, 0, 0x23ea8
	s_cmp_lg_u32 s6, -1
	s_cselect_b32 s6, s6, 0
	s_cselect_b32 s7, s41, 0
	v_mov_b32_e32 v0, s6
	s_add_i32 s6, 0, 0x23eb8
	s_cmp_lg_u32 s6, -1
	v_mov_b32_e32 v1, s7
	s_cselect_b32 s6, s6, 0
	s_cselect_b32 s7, s41, 0
	ds_read_b64 v[2:3], v0
	s_waitcnt lgkmcnt(0)
	v_mov_b32_e32 v0, s6
	v_mov_b32_e32 v1, s7
	ds_read_b64 v[4:5], v0
	s_waitcnt lgkmcnt(0)
	v_readlane_b32 s7, v255, 14
	s_mul_hi_u32 s6, s7, s14
	s_mul_i32 s6, s6, s13
	s_sub_i32 s6, s7, s6
	s_sub_i32 s7, s6, s13
	s_cmp_ge_u32 s6, s13
	s_cselect_b32 s6, s7, s6
	s_sub_i32 s7, s6, s13
	s_cmp_ge_u32 s6, s13
	s_cselect_b32 s6, s7, s6
	v_readlane_b32 s7, v255, 13
	s_xor_b32 s6, s6, s7
	s_sub_i32 s10, s6, s7
	v_mov_b32_e32 v0, v234
	s_cmpk_gt_i32 s10, 0xff
	s_waitcnt lgkmcnt(0)
	v_readfirstlane_b32 s7, v3
	v_readfirstlane_b32 s6, v2
	v_readfirstlane_b32 s9, v5
	v_readfirstlane_b32 s8, v4
	s_cbranch_scc1 .LBB0_357
	v_and_b32_e32 v5, 63, v0
	v_ashrrev_i32_e32 v7, 6, v0
	v_and_b32_e32 v9, 15, v0
	v_and_b32_e32 v0, 16, v0
	v_mov_b32_e32 v1, s9
	v_mov_b32_e32 v2, s7
	v_cmp_eq_u32_e32 vcc, 0, v0
	v_mov_b32_e32 v0, s8
	v_lshlrev_b32_e32 v184, 1, v5
	v_cndmask_b32_e32 v1, v1, v2, vcc
	v_mov_b32_e32 v2, s6
	v_cndmask_b32_e32 v0, v0, v2, vcc
	v_lshl_add_u64 v[2:3], s[0:1], 0, v[184:185]
	s_mov_b64 s[0:1], 0x3a00000
	v_lshl_add_u64 v[2:3], v[2:3], 0, s[0:1]
	s_movk_i32 s0, 0x104
	v_lshl_add_u32 v20, v5, 2, 0
	s_lshl_b32 s24, s12, 18
	v_lshlrev_b32_e32 v4, 8, v5
	v_lshlrev_b32_e32 v6, 2, v7
	v_mul_lo_u32 v21, v7, s0
	v_add_u32_e32 v13, 8, v7
	v_add_u32_e32 v15, 16, v7
	v_add_u32_e32 v17, 24, v7
	v_add_u32_e32 v19, 32, v7
	v_add_u32_e32 v22, 40, v7
	v_add_u32_e32 v23, 48, v7
	v_add_u32_e32 v24, 56, v7
	v_lshl_add_u64 v[0:1], v[0:1], 0, s[24:25]
	v_add3_u32 v11, v20, v4, v6
	v_and_b32_e32 v4, 63, v7
	v_and_b32_e32 v6, 63, v13
	v_and_b32_e32 v8, 63, v15
	v_and_b32_e32 v10, 63, v17
	v_and_b32_e32 v12, 63, v19
	v_and_b32_e32 v14, 63, v22
	v_and_b32_e32 v16, 63, v23
	v_and_b32_e32 v18, 63, v24
	v_add_u32_e32 v25, v20, v21
	s_branch .LBB0_341
